# 8 working producer waves + write-through publish after every round
# baseline (speedup 1.0000x reference)
; __global__ void __launch_bounds__(NTHR) fwd_megakernel(Params P) {
;     extern __shared__ __attribute__((aligned(16))) unsigned char lds[];
	.amdhsa_kernel _Z14fwd_megakernel6Params
		.amdhsa_group_segment_fixed_size 16384
		.amdhsa_private_segment_fixed_size 0
		.amdhsa_kernarg_size 512
		.amdhsa_user_sgpr_count 2
		.amdhsa_user_sgpr_dispatch_ptr 0
		.amdhsa_user_sgpr_queue_ptr 0
		.amdhsa_user_sgpr_kernarg_segment_ptr 1
		.amdhsa_user_sgpr_dispatch_id 0
		.amdhsa_user_sgpr_kernarg_preload_length 0
		.amdhsa_user_sgpr_kernarg_preload_offset 0
		.amdhsa_user_sgpr_private_segment_size 0
		.amdhsa_uses_dynamic_stack 0
		.amdhsa_enable_private_segment 0
		.amdhsa_system_sgpr_workgroup_id_x 1
		.amdhsa_system_sgpr_workgroup_id_y 0
		.amdhsa_system_sgpr_workgroup_id_z 0
		.amdhsa_system_sgpr_workgroup_info 0
		.amdhsa_system_vgpr_workitem_id 2
		.amdhsa_next_free_vgpr 256
		.amdhsa_next_free_sgpr 100
		.amdhsa_accum_offset 256
		.amdhsa_reserve_vcc 1
		.amdhsa_float_round_mode_32 0
		.amdhsa_float_round_mode_16_64 0
		.amdhsa_float_denorm_mode_32 3
		.amdhsa_float_denorm_mode_16_64 3
		.amdhsa_dx10_clamp 1
		.amdhsa_ieee_mode 1
		.amdhsa_fp16_overflow 0
		.amdhsa_tg_split 0
		.amdhsa_exception_fp_ieee_invalid_op 0
		.amdhsa_exception_fp_denorm_src 0
		.amdhsa_exception_fp_ieee_div_zero 0
		.amdhsa_exception_fp_ieee_overflow 0
		.amdhsa_exception_fp_ieee_underflow 0
		.amdhsa_exception_fp_ieee_inexact 0
		.amdhsa_exception_int_div_zero 0
	.end_amdhsa_kernel

; __global__ void __launch_bounds__(NTHR) fwd_megakernel(Params P) {
;     extern __shared__ __attribute__((aligned(16))) unsigned char lds[];
amdhsa.kernels:
  - .agpr_count:     0
    .args:
      - .offset:         0
        .size:           256
        .value_kind:     by_value
      - .offset:         256
        .size:           4
        .value_kind:     hidden_block_count_x
      - .offset:         260
        .size:           4
        .value_kind:     hidden_block_count_y
      - .offset:         264
        .size:           4
        .value_kind:     hidden_block_count_z
      - .offset:         268
        .size:           2
        .value_kind:     hidden_group_size_x
      - .offset:         270
        .size:           2
        .value_kind:     hidden_group_size_y
      - .offset:         272
        .size:           2
        .value_kind:     hidden_group_size_z
      - .offset:         274
        .size:           2
        .value_kind:     hidden_remainder_x
      - .offset:         276
        .size:           2
        .value_kind:     hidden_remainder_y
      - .offset:         278
        .size:           2
        .value_kind:     hidden_remainder_z
      - .offset:         296
        .size:           8
        .value_kind:     hidden_global_offset_x
      - .offset:         304
        .size:           8
        .value_kind:     hidden_global_offset_y
      - .offset:         312
        .size:           8
        .value_kind:     hidden_global_offset_z
      - .offset:         320
        .size:           2
        .value_kind:     hidden_grid_dims
      - .offset:         344
        .size:           8
        .value_kind:     hidden_multigrid_sync_arg
      - .offset:         376
        .size:           4
        .value_kind:     hidden_dynamic_lds_size
    .group_segment_fixed_size: 16384
    .kernarg_segment_align: 8
    .kernarg_segment_size: 512
    .language:       OpenCL C
    .language_version:
      - 2
      - 0
    .max_flat_workgroup_size: 512
    .name:           _Z14fwd_megakernel6Params
    .private_segment_fixed_size: 0
    .sgpr_count:     106
    .sgpr_spill_count: 171
    .symbol:         _Z14fwd_megakernel6Params.kd
    .uniform_work_group_size: 1
    .uses_dynamic_stack: false
    .vgpr_count:     256
    .vgpr_spill_count: 0
    .wavefront_size: 64
